# SB lane^32 exchanges via v_permlane32_swap + cndmask instead of ds_bpermute (on top of v12, clamp constant in a VGPR)
# baseline (speedup 1.0000x reference)
.LBB0_942:
	v_readlane_b32 s4, v255, 15
	v_readlane_b32 s5, v255, 16
	v_mov_b32_e32 v0, v157
	s_andn2_b64 vcc, exec, s[4:5]
	s_waitcnt lgkmcnt(0)
	s_cbranch_vccnz .LBB0_1005
	s_mov_b32 s98, 0
	s_mov_b32 s99, -1
	s_load_dword s4, s[34:35], 0x0
	v_ashrrev_i32_e32 v120, 3, v0
	v_ashrrev_i32_e32 v121, 31, v120
	v_and_b32_e32 v1, 7, v0
	v_lshlrev_b32_e32 v128, 4, v1
	s_waitcnt lgkmcnt(0)
	s_lshr_b32 s83, s4, 3
	v_readlane_b32 s4, v255, 27
	v_readlane_b32 s5, v255, 28
	v_readlane_b32 s6, v255, 19
	v_readlane_b32 s8, v255, 5
	v_lshl_add_u64 v[6:7], v[120:121], 0, s[4:5]
	v_lshlrev_b64 v[6:7], 13, v[6:7]
	v_lshl_add_u64 v[6:7], s[26:27], 0, v[6:7]
	v_lshl_add_u64 v[6:7], v[6:7], 0, v[128:129]
	s_lshl_b32 s4, s6, 1
	s_mov_b32 s5, s36
	v_lshl_add_u64 v[6:7], v[6:7], 0, s[4:5]
	v_readlane_b32 s4, v255, 31
	v_readlane_b32 s5, v255, 32
	v_readlane_b32 s9, v255, 6
	global_load_dwordx4 v[96:99], v[6:7], off offset:384
	global_load_dwordx4 v[100:103], v[6:7], off offset:256
	v_lshl_add_u64 v[8:9], v[120:121], 0, s[4:5]
	v_lshlrev_b64 v[8:9], 11, v[8:9]
	v_lshl_add_u64 v[8:9], s[8:9], 0, v[8:9]
	v_readlane_b32 s8, v255, 23
	v_lshl_add_u64 v[8:9], v[8:9], 0, v[128:129]
	v_readlane_b32 s9, v255, 24
	s_waitcnt vmcnt(7)
	v_ashrrev_i32_e32 v17, 6, v0
	v_lshlrev_b32_e32 v122, 5, v17
	v_lshl_add_u64 v[10:11], v[8:9], 0, s[8:9]
	v_readlane_b32 s8, v255, 17
	v_readlane_b32 s9, v255, 18
	v_and_b32_e32 v125, 31, v0
	v_bfe_u32 v16, v0, 5, 1
	v_lshl_add_u64 v[12:13], v[8:9], 0, s[8:9]
	v_readlane_b32 s8, v255, 25
	v_readlane_b32 s9, v255, 26
	global_load_dwordx4 v[104:107], v[10:11], off
	global_load_dwordx4 v[88:91], v[12:13], off
	v_lshl_add_u64 v[10:11], v[8:9], 0, s[8:9]
	v_readlane_b32 s8, v255, 21
	v_readlane_b32 s9, v255, 22
	global_load_dwordx4 v[84:87], v[6:7], off offset:128
	global_load_dwordx4 v[92:95], v[6:7], off
	v_lshl_add_u64 v[6:7], v[8:9], 0, s[8:9]
	global_load_dwordx4 v[108:111], v[10:11], off
	global_load_dwordx4 v[80:83], v[6:7], off
	v_add_u32_e32 v6, s6, v122
	v_or_b32_e32 v6, v6, v125
	v_ashrrev_i32_e32 v7, 31, v6
	v_lshl_add_u64 v[6:7], v[6:7], 0, s[4:5]
	v_readlane_b32 s4, v255, 33
	v_lshlrev_b64 v[6:7], 11, v[6:7]
	v_readlane_b32 s5, v255, 34
	v_lshlrev_b32_e32 v8, 4, v16
	v_mov_b32_e32 v9, v129
	v_lshl_add_u64 v[6:7], s[4:5], 0, v[6:7]
	v_lshl_add_u64 v[6:7], v[6:7], 0, v[8:9]
	global_load_dwordx4 v[64:67], v[6:7], off offset:96
	global_load_dwordx4 v[68:71], v[6:7], off offset:64
	global_load_dwordx4 v[72:75], v[6:7], off offset:32
	global_load_dwordx4 v[76:79], v[6:7], off
	v_lshrrev_b32_e32 v3, 4, v0
	v_lshlrev_b32_e32 v2, 7, v120
	v_bitop3_b32 v4, v3, v0, 7 bitop3:0x28
	v_lshl_or_b32 v127, v4, 4, v2
	v_and_b32_e32 v4, 6, v0
	v_bitop3_b32 v3, v3, v4, 7 bitop3:0x6c
	v_lshlrev_b32_e32 v4, 3, v0
	v_lshlrev_b32_e32 v3, 4, v3
	v_and_b32_e32 v4, 8, v4
	v_or3_b32 v131, v3, v2, v4
	v_add_u32_e32 v3, 0x2000, v131
	v_lshrrev_b32_e32 v5, 1, v0
	v_bfe_u32 v14, v0, 1, 3
	v_xor_b32_e32 v158, 16, v3
	v_bitop3_b32 v3, v16, v5, 7 bitop3:0x78
	v_lshlrev_b32_e32 v163, 4, v3
	v_bitop3_b32 v3, v16, v14, 2 bitop3:0x36
	v_and_b32_e32 v15, 63, v0
	v_lshlrev_b32_e32 v2, 3, v1
	v_lshlrev_b32_e32 v164, 4, v3
	v_bitop3_b32 v3, v16, v14, 4 bitop3:0x36
	v_bfe_u32 v124, v0, 3, 3
	v_lshlrev_b32_e32 v1, 1, v1
	v_cmp_eq_u32_e64 s[8:9], 0, v15
	v_cmp_gt_u32_e64 s[10:11], 32, v15
	v_lshlrev_b32_e32 v165, 4, v3
	v_bitop3_b32 v3, v16, v14, 6 bitop3:0x36
	v_and_b32_e32 v6, 15, v0
	v_or_b32_e32 v14, 1, v1
	v_xor_b32_e32 v15, v124, v1
	v_or_b32_e32 v132, 24, v124
	v_lshlrev_b32_e32 v4, 3, v16
	v_ashrrev_i32_e32 v159, 7, v0
	v_lshl_add_u32 v160, v17, 2, v153
	v_lshlrev_b32_e32 v162, 2, v16
	v_lshlrev_b32_e32 v166, 4, v3
	v_lshlrev_b32_e32 v3, 13, v17
	v_lshlrev_b32_e32 v5, 8, v0
	s_movk_i32 s4, 0x1f00
	v_bitop3_b32 v7, v16, v0, 15 bitop3:0x78
	v_bitop3_b32 v8, v16, v6, 2 bitop3:0x36
	v_bitop3_b32 v9, v16, v6, 4 bitop3:0x36
	v_bitop3_b32 v10, v16, v6, 6 bitop3:0x36
	v_bitop3_b32 v11, v16, v6, 8 bitop3:0x36
	v_bitop3_b32 v12, v16, v6, 10 bitop3:0x36
	v_bitop3_b32 v13, v16, v6, 12 bitop3:0x36
	v_bitop3_b32 v6, v16, v6, 14 bitop3:0x36
	v_lshlrev_b32_e32 v168, 4, v15
	v_bitop3_b32 v15, v1, v124, 1 bitop3:0x36
	v_or_b32_e32 v126, 8, v124
	v_bitop3_b32 v16, v124, v1, 8 bitop3:0x36
	v_bitop3_b32 v17, v124, v14, 8 bitop3:0x36
	v_or_b32_e32 v130, 16, v124
	v_bitop3_b32 v1, v132, v1, 15 bitop3:0x6c
	v_bitop3_b32 v14, v132, v14, 15 bitop3:0x6c
	v_lshlrev_b32_e32 v0, 4, v0
	v_and_or_b32 v5, v5, s4, v3
	v_lshlrev_b32_e32 v7, 4, v7
	v_lshlrev_b32_e32 v8, 4, v8
	v_lshlrev_b32_e32 v9, 4, v9
	v_lshlrev_b32_e32 v10, 4, v10
	v_lshlrev_b32_e32 v11, 4, v11
	v_lshlrev_b32_e32 v12, 4, v12
	v_lshlrev_b32_e32 v13, 4, v13
	v_lshlrev_b32_e32 v6, 4, v6
	v_lshl_or_b32 v167, v124, 8, v3
	v_lshlrev_b32_e32 v169, 4, v15
	v_lshl_or_b32 v15, v126, 8, v3
	v_lshlrev_b32_e32 v16, 4, v16
	v_lshlrev_b32_e32 v17, 4, v17
	v_lshl_or_b32 v170, v130, 8, v3
	v_lshl_or_b32 v3, v132, 8, v3
	v_lshlrev_b32_e32 v1, 4, v1
	v_lshlrev_b32_e32 v14, 4, v14
	v_lshl_add_u64 v[134:135], s[26:27], 0, v[128:129]
	v_and_b32_e32 v128, 0x70, v0
	v_lshlrev_b32_e32 v171, 6, v159
	v_or_b32_e32 v133, v122, v125
	v_lshlrev_b32_e32 v161, 7, v125
	v_ashrrev_i32_e32 v123, 31, v122
	v_lshl_add_u64 v[136:137], s[20:21], 0, v[128:129]
	v_or_b32_e32 v173, v171, v162
	v_lshlrev_b32_e32 v174, 14, v159
	v_lshlrev_b32_e32 v128, 1, v2
	v_lshlrev_b32_e32 v138, 1, v4
	v_add_u32_e32 v175, v5, v7
	v_add_u32_e32 v176, v5, v8
	v_add_u32_e32 v177, v5, v9
	v_add_u32_e32 v178, v5, v10
	v_add_u32_e32 v179, v5, v11
	v_add_u32_e32 v180, v5, v12
	v_add_u32_e32 v181, v5, v13
	v_add_u32_e32 v182, v5, v6
	v_add_u32_e32 v183, v15, v16
	v_add_u32_e32 v184, v15, v17
	v_add_u32_e32 v185, v3, v1
	v_add_u32_e32 v186, v3, v14
	v_readlane_b32 s66, v255, 7
	s_waitcnt vmcnt(0)
	s_branch .LBB0_945

.LBB0_968:
	s_or_b64 exec, exec, s[6:7]
	v_or_b32_e32 v6, v0, v162
	v_or_b32_e32 v0, 63, v0
	v_cmp_lt_i32_e64 s[14:15], v0, v139
	v_mov_b32_e32 v147, 1.0
	s_mov_b64 s[6:7], 0
	s_and_saveexec_b64 s[38:39], vcc
	s_cbranch_execz .LBB0_970
	s_nop 3
	v_max_f32_e64 v0, -v32, -v32
	v_min_f32_e32 v0, 0x42fc0000, v0
	v_exp_f32_e32 v0, v0
	v_max_f32_e64 v1, -v33, -v33
	v_min_f32_e32 v1, 0x42fc0000, v1
	v_exp_f32_e32 v1, v1
	v_add_f32_e32 v2, 1.0, v0
	v_rcp_f32_e32 v3, v2
	v_or_b32_e32 v2, 32, v6
	v_cmp_lt_i32_e64 s[18:19], v2, v187
	v_add_f32_e32 v2, 1.0, v1
	v_rcp_f32_e32 v4, v2
	v_mul_f32_e32 v0, v0, v3
	s_or_b64 s[18:19], s[14:15], s[18:19]
	v_cndmask_b32_e64 v2, 1.0, v0, s[18:19]
	v_mul_f32_e32 v0, v1, v4
	v_or_b32_e32 v1, 33, v6
	v_cndmask_b32_e64 v7, 0, v3, s[18:19]
	v_cmp_lt_i32_e64 s[18:19], v1, v187
	v_max_f32_e64 v1, -v34, -v34
	s_or_b64 s[18:19], s[14:15], s[18:19]
	v_min_f32_e32 v1, 0x42fc0000, v1
	v_cndmask_b32_e64 v12, 0, v4, s[18:19]
	v_max_f32_e64 v4, -v35, -v35
	v_exp_f32_e32 v1, v1
	v_min_f32_e32 v4, 0x42fc0000, v4
	v_exp_f32_e32 v5, v4
	v_or_b32_e32 v4, 34, v6
	v_add_f32_e32 v3, 1.0, v1
	v_cndmask_b32_e64 v0, 1.0, v0, s[18:19]
	v_rcp_f32_e32 v3, v3
	v_cmp_lt_i32_e64 s[18:19], v4, v187
	v_add_f32_e32 v4, 1.0, v5
	v_rcp_f32_e32 v9, v4
	s_or_b64 s[18:19], s[14:15], s[18:19]
	v_mul_f32_e32 v1, v1, v3
	v_cndmask_b32_e64 v13, 0, v3, s[18:19]
	v_or_b32_e32 v3, 35, v6
	v_cndmask_b32_e64 v4, 1.0, v1, s[18:19]
	v_mul_f32_e32 v1, v5, v9
	v_cmp_lt_i32_e64 s[18:19], v3, v187
	v_max_f32_e64 v3, -v36, -v36
	v_max_f32_e64 v5, -v37, -v37
	v_min_f32_e32 v3, 0x42fc0000, v3
	v_min_f32_e32 v5, 0x42fc0000, v5
	v_exp_f32_e32 v3, v3
	v_exp_f32_e32 v5, v5
	s_or_b64 s[18:19], s[14:15], s[18:19]
	v_cndmask_b32_e64 v14, 0, v9, s[18:19]
	v_or_b32_e32 v9, 40, v6
	v_cndmask_b32_e64 v8, 1.0, v1, s[18:19]
	v_add_f32_e32 v1, 1.0, v3
	v_cmp_lt_i32_e64 s[18:19], v9, v187
	v_add_f32_e32 v9, 1.0, v5
	v_rcp_f32_e32 v1, v1
	v_rcp_f32_e32 v9, v9
	s_or_b64 s[18:19], s[14:15], s[18:19]
	v_or_b32_e32 v10, 42, v6
	v_mul_f32_e32 v3, v3, v1
	v_cndmask_b32_e64 v15, 0, v1, s[18:19]
	v_mul_f32_e32 v1, v5, v9
	v_or_b32_e32 v5, 41, v6
	v_cndmask_b32_e64 v3, 1.0, v3, s[18:19]
	v_cmp_lt_i32_e64 s[18:19], v5, v187
	v_max_f32_e64 v5, -v38, -v38
	v_min_f32_e32 v5, 0x42fc0000, v5
	s_or_b64 s[18:19], s[14:15], s[18:19]
	v_exp_f32_e32 v5, v5
	v_cndmask_b32_e64 v17, 0, v9, s[18:19]
	v_max_f32_e64 v9, -v39, -v39
	v_min_f32_e32 v9, 0x42fc0000, v9
	v_exp_f32_e32 v9, v9
	v_cndmask_b32_e64 v16, 1.0, v1, s[18:19]
	v_add_f32_e32 v1, 1.0, v5
	v_rcp_f32_e32 v1, v1
	v_cmp_lt_i32_e64 s[18:19], v10, v187
	v_add_f32_e32 v10, 1.0, v9
	v_rcp_f32_e32 v10, v10
	v_mul_f32_e32 v5, v5, v1
	s_or_b64 s[18:19], s[14:15], s[18:19]
	v_cndmask_b32_e64 v18, 1.0, v5, s[18:19]
	v_or_b32_e32 v5, 43, v6
	v_cndmask_b32_e64 v19, 0, v1, s[18:19]
	v_mul_f32_e32 v1, v9, v10
	v_cmp_lt_i32_e64 s[18:19], v5, v187
	v_max_f32_e64 v5, -v40, -v40
	v_max_f32_e64 v9, -v41, -v41
	v_min_f32_e32 v5, 0x42fc0000, v5
	v_min_f32_e32 v9, 0x42fc0000, v9
	v_exp_f32_e32 v5, v5
	v_exp_f32_e32 v9, v9
	s_or_b64 s[18:19], s[14:15], s[18:19]
	v_cndmask_b32_e64 v21, 0, v10, s[18:19]
	v_or_b32_e32 v10, 48, v6
	v_cndmask_b32_e64 v20, 1.0, v1, s[18:19]
	v_add_f32_e32 v1, 1.0, v5
	v_cmp_lt_i32_e64 s[18:19], v10, v187
	v_add_f32_e32 v10, 1.0, v9
	v_rcp_f32_e32 v1, v1
	v_rcp_f32_e32 v10, v10
	s_or_b64 s[18:19], s[14:15], s[18:19]
	v_max_f32_e64 v23, -v43, -v43
	v_mul_f32_e32 v5, v5, v1
	v_cndmask_b32_e64 v11, 0, v1, s[18:19]
	v_mul_f32_e32 v1, v9, v10
	v_or_b32_e32 v9, 49, v6
	v_cndmask_b32_e64 v5, 1.0, v5, s[18:19]
	v_cmp_lt_i32_e64 s[18:19], v9, v187
	v_max_f32_e64 v9, -v42, -v42
	v_min_f32_e32 v9, 0x42fc0000, v9
	v_exp_f32_e32 v9, v9
	s_or_b64 s[18:19], s[14:15], s[18:19]
	v_cndmask_b32_e64 v22, 1.0, v1, s[18:19]
	v_min_f32_e32 v23, 0x42fc0000, v23
	v_add_f32_e32 v1, 1.0, v9
	v_rcp_f32_e32 v1, v1
	v_exp_f32_e32 v23, v23
	v_or_b32_e32 v24, 50, v6
	v_cndmask_b32_e64 v10, 0, v10, s[18:19]
	v_cmp_lt_i32_e64 s[18:19], v24, v187
	v_mul_f32_e32 v9, v9, v1
	s_or_b64 s[18:19], s[14:15], s[18:19]
	v_cndmask_b32_e64 v25, 1.0, v9, s[18:19]
	v_or_b32_e32 v9, 51, v6
	v_add_f32_e32 v24, 1.0, v23
	v_cndmask_b32_e64 v26, 0, v1, s[18:19]
	v_cmp_lt_i32_e64 s[18:19], v9, v187
	v_max_f32_e64 v9, -v44, -v44
	v_max_f32_e64 v27, -v45, -v45
	v_rcp_f32_e32 v24, v24
	v_min_f32_e32 v9, 0x42fc0000, v9
	v_min_f32_e32 v27, 0x42fc0000, v27
	v_exp_f32_e32 v9, v9
	v_exp_f32_e32 v27, v27
	v_mul_f32_e32 v1, v23, v24
	s_or_b64 s[18:19], s[14:15], s[18:19]
	v_or_b32_e32 v28, 56, v6
	v_cndmask_b32_e64 v23, 1.0, v1, s[18:19]
	v_cndmask_b32_e64 v24, 0, v24, s[18:19]
	v_add_f32_e32 v1, 1.0, v9
	v_cmp_lt_i32_e64 s[18:19], v28, v187
	v_add_f32_e32 v28, 1.0, v27
	v_rcp_f32_e32 v1, v1
	v_rcp_f32_e32 v28, v28
	s_or_b64 s[18:19], s[14:15], s[18:19]
	v_max_f32_e64 v31, -v47, -v47
	v_mul_f32_e32 v9, v9, v1
	v_cndmask_b32_e64 v29, 0, v1, s[18:19]
	v_mul_f32_e32 v1, v27, v28
	v_or_b32_e32 v27, 57, v6
	v_cndmask_b32_e64 v9, 1.0, v9, s[18:19]
	v_cmp_lt_i32_e64 s[18:19], v27, v187
	v_max_f32_e64 v27, -v46, -v46
	v_min_f32_e32 v27, 0x42fc0000, v27
	v_min_f32_e32 v31, 0x42fc0000, v31
	v_exp_f32_e32 v27, v27
	v_exp_f32_e32 v31, v31
	s_or_b64 s[18:19], s[14:15], s[18:19]
	v_or_b32_e32 v32, 58, v6
	v_cndmask_b32_e64 v30, 1.0, v1, s[18:19]
	v_cndmask_b32_e64 v28, 0, v28, s[18:19]
	v_add_f32_e32 v1, 1.0, v27
	v_cmp_lt_i32_e64 s[18:19], v32, v187
	v_add_f32_e32 v32, 1.0, v31
	v_rcp_f32_e32 v1, v1
	v_rcp_f32_e32 v32, v32
	s_or_b64 s[18:19], s[14:15], s[18:19]
	v_and_b32_e32 v34, 64, v172
	v_mul_f32_e32 v27, v27, v1
	v_cndmask_b32_e64 v33, 0, v1, s[18:19]
	v_mul_f32_e32 v1, v31, v32
	v_or_b32_e32 v31, 59, v6
	v_cndmask_b32_e64 v27, 1.0, v27, s[18:19]
	v_cmp_lt_i32_e64 s[18:19], v31, v187
	s_or_b64 s[18:19], s[14:15], s[18:19]
	v_add_u32_e32 v34, 64, v34
	v_cndmask_b32_e64 v31, 1.0, v1, s[18:19]
	v_xor_b32_e32 v1, 32, v172
	v_cndmask_b32_e64 v32, 0, v32, s[18:19]
	v_cmp_lt_i32_e64 s[18:19], v1, v34
	v_mul_f32_e32 v9, v9, v30
	v_mul_f32_e32 v35, v27, v31
	v_cndmask_b32_e64 v1, v172, v1, s[18:19]
	v_lshlrev_b32_e32 v34, 2, v1
	v_mul_f32_e32 v9, v9, v35
	v_mov_b32_e32 v149, v9
	v_mov_b32_e32 v35, v9
	s_nop 1
	v_permlane32_swap_b32_e32 v35, v149
	v_cndmask_b32_e64 v35, v149, v35, s[98:99]
	v_mul_f32_e32 v5, v5, v22
	v_mul_f32_e32 v36, v25, v23
	v_mul_f32_e32 v5, v5, v36
	v_mov_b32_e32 v149, v5
	v_mov_b32_e32 v36, v5
	s_nop 1
	v_permlane32_swap_b32_e32 v36, v149
	v_cndmask_b32_e64 v36, v149, v36, s[98:99]
	s_waitcnt lgkmcnt(1)
	v_cndmask_b32_e64 v37, 1.0, v35, s[10:11]
	v_mul_f32_e32 v31, v31, v37
	v_mul_f32_e32 v1, v3, v16
	v_mul_f32_e32 v3, v18, v20
	v_mul_f32_e32 v27, v27, v31
	v_mul_f32_e32 v3, v1, v3
	v_mul_f32_e32 v45, v28, v27
	v_mul_f32_e32 v27, v30, v27
	v_mul_f32_e32 v9, v9, v35
	v_mov_b32_e32 v149, v3
	v_mov_b32_e32 v1, v3
	s_nop 1
	v_permlane32_swap_b32_e32 v1, v149
	v_cndmask_b32_e64 v1, v149, v1, s[98:99]
	v_mul_f32_e32 v44, v29, v27
	s_waitcnt lgkmcnt(1)
	v_mul_f32_e32 v27, v9, v36
	v_cndmask_b32_e64 v27, v9, v27, s[10:11]
	v_mul_f32_e32 v23, v23, v27
	v_mul_f32_e32 v42, v26, v23
	v_mul_f32_e32 v23, v25, v23
	v_mul_f32_e32 v41, v10, v23
	v_mul_f32_e32 v10, v22, v23
	v_mul_f32_e32 v5, v5, v36
	v_mul_f32_e32 v40, v11, v10
	v_pk_mul_f32 v[10:11], v[4:5], v[8:9]
	s_waitcnt lgkmcnt(0)
	v_pk_mul_f32 v[2:3], v[2:3], v[0:1]
	v_mul_f32_e32 v1, v11, v1
	v_pk_mul_f32 v[2:3], v[2:3], v[10:11]
	v_mov_b32_e32 v149, v2
	v_mov_b32_e32 v5, v2
	s_nop 1
	v_permlane32_swap_b32_e32 v5, v149
	v_cndmask_b32_e64 v5, v149, v5, s[98:99]
	v_cndmask_b32_e64 v1, v11, v1, s[10:11]
	v_mul_f32_e32 v39, v21, v1
	v_mul_f32_e32 v1, v20, v1
	v_mul_f32_e32 v38, v19, v1
	v_mul_f32_e32 v1, v18, v1
	v_mul_f32_e32 v47, v32, v37
	v_mul_f32_e32 v37, v17, v1
	v_mul_f32_e32 v1, v16, v1
	v_mul_f32_e32 v36, v15, v1
	s_waitcnt lgkmcnt(0)
	v_mul_f32_e32 v1, v3, v5
	v_cndmask_b32_e64 v1, v3, v1, s[10:11]
	v_mul_f32_e32 v35, v14, v1
	v_mul_f32_e32 v1, v8, v1
	v_mul_f32_e32 v34, v13, v1
	v_mul_f32_e32 v1, v4, v1
	v_mul_f32_e32 v0, v0, v1
	v_mul_f32_e32 v32, v7, v0
	v_mul_f32_e32 v0, v2, v5
	v_mul_f32_e32 v147, v0, v3
	v_cmp_gt_f32_e64 s[18:19], s81, v147
	s_cmp_eq_u64 s[18:19], exec
	s_cselect_b64 s[6:7], -1, 0
	v_mul_f32_e32 v46, v33, v31
	v_mul_f32_e32 v43, v24, v27
	v_mul_f32_e32 v33, v12, v1
	s_and_b64 s[6:7], s[6:7], exec
.LBB0_970:
	s_or_b64 exec, exec, s[38:39]
	s_mov_b64 s[18:19], -1
	s_xor_b64 s[38:39], s[6:7], -1
	s_and_saveexec_b64 s[40:41], s[38:39]
	s_cbranch_execz .LBB0_972
	v_max_f32_e64 v0, -v48, -v48
	v_min_f32_e32 v0, 0x42fc0000, v0
	v_max_f32_e64 v1, -v49, -v49
	v_exp_f32_e32 v0, v0
	v_min_f32_e32 v1, 0x42fc0000, v1
	v_exp_f32_e32 v1, v1
	v_cmp_lt_i32_e64 s[18:19], v6, v187
	v_add_f32_e32 v2, 1.0, v0
	v_rcp_f32_e32 v3, v2
	v_add_f32_e32 v2, 1.0, v1
	v_rcp_f32_e32 v4, v2
	s_or_b64 s[18:19], s[14:15], s[18:19]
	v_mul_f32_e32 v0, v0, v3
	v_cndmask_b32_e64 v2, 1.0, v0, s[18:19]
	v_mul_f32_e32 v0, v1, v4
	v_or_b32_e32 v1, 1, v6
	v_cndmask_b32_e64 v10, 0, v3, s[18:19]
	v_cmp_lt_i32_e64 s[18:19], v1, v187
	v_max_f32_e64 v1, -v50, -v50
	s_or_b64 s[18:19], s[14:15], s[18:19]
	v_min_f32_e32 v1, 0x42fc0000, v1
	v_cndmask_b32_e64 v11, 0, v4, s[18:19]
	v_max_f32_e64 v4, -v51, -v51
	v_exp_f32_e32 v1, v1
	v_min_f32_e32 v4, 0x42fc0000, v4
	v_exp_f32_e32 v5, v4
	v_or_b32_e32 v4, 2, v6
	v_add_f32_e32 v3, 1.0, v1
	v_cndmask_b32_e64 v0, 1.0, v0, s[18:19]
	v_rcp_f32_e32 v3, v3
	v_cmp_lt_i32_e64 s[18:19], v4, v187
	v_add_f32_e32 v4, 1.0, v5
	v_rcp_f32_e32 v7, v4
	s_or_b64 s[18:19], s[14:15], s[18:19]
	v_mul_f32_e32 v1, v1, v3
	v_cndmask_b32_e64 v12, 0, v3, s[18:19]
	v_or_b32_e32 v3, 3, v6
	v_cndmask_b32_e64 v4, 1.0, v1, s[18:19]
	v_mul_f32_e32 v1, v5, v7
	v_cmp_lt_i32_e64 s[18:19], v3, v187
	v_max_f32_e64 v3, -v52, -v52
	v_max_f32_e64 v5, -v53, -v53
	v_min_f32_e32 v3, 0x42fc0000, v3
	v_min_f32_e32 v5, 0x42fc0000, v5
	v_exp_f32_e32 v3, v3
	v_exp_f32_e32 v5, v5
	s_or_b64 s[18:19], s[14:15], s[18:19]
	v_cndmask_b32_e64 v13, 0, v7, s[18:19]
	v_or_b32_e32 v7, 8, v6
	v_cndmask_b32_e64 v8, 1.0, v1, s[18:19]
	v_add_f32_e32 v1, 1.0, v3
	v_cmp_lt_i32_e64 s[18:19], v7, v187
	v_add_f32_e32 v7, 1.0, v5
	v_rcp_f32_e32 v1, v1
	v_rcp_f32_e32 v7, v7
	s_or_b64 s[18:19], s[14:15], s[18:19]
	v_or_b32_e32 v9, 10, v6
	v_mul_f32_e32 v3, v3, v1
	v_cndmask_b32_e64 v14, 0, v1, s[18:19]
	v_mul_f32_e32 v1, v5, v7
	v_or_b32_e32 v5, 9, v6
	v_cndmask_b32_e64 v3, 1.0, v3, s[18:19]
	v_cmp_lt_i32_e64 s[18:19], v5, v187
	v_max_f32_e64 v5, -v54, -v54
	v_min_f32_e32 v5, 0x42fc0000, v5
	s_or_b64 s[18:19], s[14:15], s[18:19]
	v_exp_f32_e32 v5, v5
	v_cndmask_b32_e64 v16, 0, v7, s[18:19]
	v_max_f32_e64 v7, -v55, -v55
	v_min_f32_e32 v7, 0x42fc0000, v7
	v_exp_f32_e32 v7, v7
	v_cndmask_b32_e64 v15, 1.0, v1, s[18:19]
	v_add_f32_e32 v1, 1.0, v5
	v_rcp_f32_e32 v1, v1
	v_cmp_lt_i32_e64 s[18:19], v9, v187
	v_add_f32_e32 v9, 1.0, v7
	v_rcp_f32_e32 v9, v9
	v_mul_f32_e32 v5, v5, v1
	s_or_b64 s[18:19], s[14:15], s[18:19]
	v_cndmask_b32_e64 v17, 1.0, v5, s[18:19]
	v_or_b32_e32 v5, 11, v6
	v_cndmask_b32_e64 v18, 0, v1, s[18:19]
	v_mul_f32_e32 v1, v7, v9
	v_cmp_lt_i32_e64 s[18:19], v5, v187
	v_max_f32_e64 v5, -v56, -v56
	v_max_f32_e64 v7, -v57, -v57
	v_min_f32_e32 v5, 0x42fc0000, v5
	v_min_f32_e32 v7, 0x42fc0000, v7
	v_exp_f32_e32 v5, v5
	v_exp_f32_e32 v7, v7
	s_or_b64 s[18:19], s[14:15], s[18:19]
	v_cndmask_b32_e64 v20, 0, v9, s[18:19]
	v_or_b32_e32 v9, 16, v6
	v_cndmask_b32_e64 v19, 1.0, v1, s[18:19]
	v_add_f32_e32 v1, 1.0, v5
	v_cmp_lt_i32_e64 s[18:19], v9, v187
	v_add_f32_e32 v9, 1.0, v7
	v_rcp_f32_e32 v1, v1
	v_rcp_f32_e32 v9, v9
	s_or_b64 s[18:19], s[14:15], s[18:19]
	v_or_b32_e32 v24, 18, v6
	v_mul_f32_e32 v5, v5, v1
	v_cndmask_b32_e64 v21, 0, v1, s[18:19]
	v_mul_f32_e32 v1, v7, v9
	v_or_b32_e32 v7, 17, v6
	v_cndmask_b32_e64 v5, 1.0, v5, s[18:19]
	v_cmp_lt_i32_e64 s[18:19], v7, v187
	s_or_b64 s[18:19], s[14:15], s[18:19]
	v_max_f32_e64 v7, -v58, -v58
	v_cndmask_b32_e64 v23, 0, v9, s[18:19]
	v_max_f32_e64 v9, -v59, -v59
	v_min_f32_e32 v7, 0x42fc0000, v7
	v_min_f32_e32 v9, 0x42fc0000, v9
	v_exp_f32_e32 v7, v7
	v_exp_f32_e32 v9, v9
	v_cndmask_b32_e64 v22, 1.0, v1, s[18:19]
	v_cmp_lt_i32_e64 s[18:19], v24, v187
	v_add_f32_e32 v1, 1.0, v7
	v_add_f32_e32 v24, 1.0, v9
	v_rcp_f32_e32 v1, v1
	v_rcp_f32_e32 v24, v24
	s_or_b64 s[18:19], s[14:15], s[18:19]
	v_max_f32_e64 v27, -v61, -v61
	v_mul_f32_e32 v7, v7, v1
	v_cndmask_b32_e64 v25, 0, v1, s[18:19]
	v_mul_f32_e32 v1, v9, v24
	v_or_b32_e32 v9, 19, v6
	v_cndmask_b32_e64 v7, 1.0, v7, s[18:19]
	v_cmp_lt_i32_e64 s[18:19], v9, v187
	v_max_f32_e64 v9, -v60, -v60
	v_min_f32_e32 v9, 0x42fc0000, v9
	v_min_f32_e32 v27, 0x42fc0000, v27
	v_exp_f32_e32 v9, v9
	v_exp_f32_e32 v27, v27
	s_or_b64 s[18:19], s[14:15], s[18:19]
	v_or_b32_e32 v28, 24, v6
	v_cndmask_b32_e64 v26, 1.0, v1, s[18:19]
	v_cndmask_b32_e64 v24, 0, v24, s[18:19]
	v_add_f32_e32 v1, 1.0, v9
	v_cmp_lt_i32_e64 s[18:19], v28, v187
	v_add_f32_e32 v28, 1.0, v27
	v_rcp_f32_e32 v1, v1
	v_rcp_f32_e32 v28, v28
	s_or_b64 s[18:19], s[14:15], s[18:19]
	v_max_f32_e64 v31, -v63, -v63
	v_mul_f32_e32 v9, v9, v1
	v_cndmask_b32_e64 v29, 0, v1, s[18:19]
	v_mul_f32_e32 v1, v27, v28
	v_or_b32_e32 v27, 25, v6
	v_cndmask_b32_e64 v9, 1.0, v9, s[18:19]
	v_cmp_lt_i32_e64 s[18:19], v27, v187
	v_max_f32_e64 v27, -v62, -v62
	v_min_f32_e32 v27, 0x42fc0000, v27
	v_exp_f32_e32 v27, v27
	v_min_f32_e32 v31, 0x42fc0000, v31
	s_or_b64 s[18:19], s[14:15], s[18:19]
	v_exp_f32_e32 v31, v31
	v_cndmask_b32_e64 v30, 1.0, v1, s[18:19]
	v_add_f32_e32 v1, 1.0, v27
	v_rcp_f32_e32 v1, v1
	v_or_b32_e32 v48, 26, v6
	v_cndmask_b32_e64 v28, 0, v28, s[18:19]
	v_cmp_lt_i32_e64 s[18:19], v48, v187
	v_add_f32_e32 v48, 1.0, v31
	v_rcp_f32_e32 v48, v48
	v_mul_f32_e32 v27, v27, v1
	s_or_b64 s[18:19], s[14:15], s[18:19]
	v_or_b32_e32 v6, 27, v6
	v_cndmask_b32_e64 v27, 1.0, v27, s[18:19]
	v_cndmask_b32_e64 v49, 0, v1, s[18:19]
	v_cmp_lt_i32_e64 s[18:19], v6, v187
	s_or_b64 s[14:15], s[14:15], s[18:19]
	v_mul_f32_e32 v1, v31, v48
	v_cndmask_b32_e64 v31, 0, v48, s[14:15]
	v_and_b32_e32 v48, 64, v172
	v_cndmask_b32_e64 v6, 1.0, v1, s[14:15]
	v_xor_b32_e32 v1, 32, v172
	v_add_u32_e32 v48, 64, v48
	v_cmp_lt_i32_e64 s[14:15], v1, v48
	v_mul_f32_e32 v9, v9, v30
	v_mul_f32_e32 v50, v27, v6
	v_cndmask_b32_e64 v1, v172, v1, s[14:15]
	v_lshlrev_b32_e32 v48, 2, v1
	v_mul_f32_e32 v9, v9, v50
	v_mov_b32_e32 v149, v9
	v_mov_b32_e32 v50, v9
	s_nop 1
	v_permlane32_swap_b32_e32 v50, v149
	v_cndmask_b32_e64 v50, v149, v50, s[98:99]
	v_mul_f32_e32 v5, v5, v22
	v_mul_f32_e32 v51, v7, v26
	v_mul_f32_e32 v5, v5, v51
	v_mov_b32_e32 v149, v5
	v_mov_b32_e32 v51, v5
	s_nop 1
	v_permlane32_swap_b32_e32 v51, v149
	v_cndmask_b32_e64 v51, v149, v51, s[98:99]
	s_waitcnt lgkmcnt(1)
	v_mul_f32_e32 v52, v147, v50
	v_cndmask_b32_e64 v52, v147, v52, s[10:11]
	v_mul_f32_e32 v6, v6, v52
	v_mul_f32_e32 v62, v49, v6
	v_mul_f32_e32 v6, v27, v6
	v_mul_f32_e32 v61, v28, v6
	v_mul_f32_e32 v6, v30, v6
	v_mul_f32_e32 v1, v3, v15
	v_mul_f32_e32 v3, v17, v19
	v_mul_f32_e32 v60, v29, v6
	v_mul_f32_e32 v6, v9, v50
	v_mul_f32_e32 v3, v1, v3
	v_mul_f32_e32 v9, v147, v6
	v_mov_b32_e32 v149, v3
	v_mov_b32_e32 v1, v3
	s_nop 1
	v_permlane32_swap_b32_e32 v1, v149
	v_cndmask_b32_e64 v1, v149, v1, s[98:99]
	s_waitcnt lgkmcnt(1)
	v_mul_f32_e32 v6, v9, v51
	v_cndmask_b32_e64 v6, v9, v6, s[10:11]
	v_mul_f32_e32 v59, v24, v6
	v_mul_f32_e32 v6, v26, v6
	v_mul_f32_e32 v58, v25, v6
	v_mul_f32_e32 v6, v7, v6
	v_mul_f32_e32 v57, v23, v6
	v_mul_f32_e32 v6, v22, v6
	v_mul_f32_e32 v5, v5, v51
	v_mul_f32_e32 v56, v21, v6
	v_pk_mul_f32 v[6:7], v[4:5], v[8:9]
	s_waitcnt lgkmcnt(0)
	v_pk_mul_f32 v[2:3], v[2:3], v[0:1]
	v_mul_f32_e32 v1, v7, v1
	v_pk_mul_f32 v[2:3], v[2:3], v[6:7]
	v_mov_b32_e32 v149, v2
	v_mov_b32_e32 v5, v2
	s_nop 1
	v_permlane32_swap_b32_e32 v5, v149
	v_cndmask_b32_e64 v5, v149, v5, s[98:99]
	v_cndmask_b32_e64 v1, v7, v1, s[10:11]
	v_mul_f32_e32 v55, v20, v1
	v_mul_f32_e32 v1, v19, v1
	v_mul_f32_e32 v54, v18, v1
	v_mul_f32_e32 v1, v17, v1
	v_mul_f32_e32 v53, v16, v1
	v_mul_f32_e32 v1, v15, v1
	v_mul_f32_e32 v63, v31, v52
	v_mul_f32_e32 v52, v14, v1
	s_waitcnt lgkmcnt(0)
	v_mul_f32_e32 v1, v3, v5
	v_cndmask_b32_e64 v1, v3, v1, s[10:11]
	v_mul_f32_e32 v51, v13, v1
	v_mul_f32_e32 v1, v8, v1
	v_mul_f32_e32 v50, v12, v1
	v_mul_f32_e32 v1, v4, v1
	v_mul_f32_e32 v0, v0, v1
	v_mul_f32_e32 v48, v10, v0
	v_mul_f32_e32 v0, v2, v5
	v_mul_f32_e32 v147, v0, v3
	v_cmp_gt_f32_e64 s[14:15], s81, v147
	s_cmp_eq_u64 s[14:15], exec
	s_cselect_b64 s[6:7], -1, 0
	v_mul_f32_e32 v49, v11, v1
	s_orn2_b64 s[18:19], s[6:7], exec

.Lsb_joinA:
	v_mov_b32_e32 v149, v35
	v_mov_b32_e32 v41, v35
	s_nop 1
	v_permlane32_swap_b32_e32 v41, v149
	v_cndmask_b32_e64 v41, v149, v41, s[98:99]
	v_mul_f32_e32 v36, v36, v47
	v_mov_b32_e32 v149, v36
	v_mov_b32_e32 v210, v36
	s_nop 1
	v_permlane32_swap_b32_e32 v210, v149
	v_cndmask_b32_e64 v210, v149, v210, s[98:99]
	v_mov_b32_e32 v149, v145
	v_mov_b32_e32 v33, v145
	s_nop 1
	v_permlane32_swap_b32_e32 v33, v149
	v_cndmask_b32_e64 v33, v149, v33, s[98:99]
	s_waitcnt lgkmcnt(2)
	v_mul_f32_e32 v47, v147, v41
	v_cndmask_b32_e64 v211, v147, v47, s[10:11]
	v_mul_f32_e32 v35, v35, v41
	v_mul_f32_e32 v45, v45, v211
	v_mul_f32_e32 v35, v147, v35
	v_mul_f32_e32 v43, v43, v45
	s_waitcnt lgkmcnt(1)
	v_mul_f32_e32 v41, v35, v210
	v_mul_f32_e32 v47, v46, v211
	v_mul_f32_e32 v46, v208, v45
	v_mul_f32_e32 v45, v44, v43
	v_mul_f32_e32 v43, v207, v43
	v_cndmask_b32_e64 v41, v35, v41, s[10:11]
	v_mul_f32_e32 v44, v206, v43
	v_mul_f32_e32 v43, v42, v41
	v_mul_f32_e32 v41, v205, v41
	v_mul_f32_e32 v37, v37, v41
	v_mul_f32_e32 v42, v204, v41
	v_mul_f32_e32 v41, v38, v37
	v_mul_f32_e32 v37, v40, v37
	v_mul_f32_e32 v147, v36, v210
	v_mul_f32_e32 v40, v39, v37
	v_pk_mul_f32 v[36:37], v[146:147], v[34:35]
	s_waitcnt lgkmcnt(0)
	v_pk_mul_f32 v[38:39], v[144:145], v[32:33]
	v_mul_f32_e32 v33, v37, v33
	v_pk_mul_f32 v[144:145], v[38:39], v[36:37]
	v_mov_b32_e32 v149, v144
	v_mov_b32_e32 v147, v144
	s_nop 1
	v_permlane32_swap_b32_e32 v147, v149
	v_cndmask_b32_e64 v147, v149, v147, s[98:99]
	v_cndmask_b32_e64 v33, v37, v33, s[10:11]
	v_mul_f32_e32 v39, v203, v33
	v_mul_f32_e32 v33, v202, v33
	v_mul_f32_e32 v38, v201, v33
	v_mul_f32_e32 v33, v200, v33
	v_mul_f32_e32 v37, v199, v33
	v_mul_f32_e32 v33, v198, v33
	v_mul_f32_e32 v36, v197, v33
	s_waitcnt lgkmcnt(0)
	v_mul_f32_e32 v33, v145, v147
	v_mul_f32_e32 v144, v144, v147
	v_cndmask_b32_e64 v33, v145, v33, s[10:11]
	v_mul_f32_e32 v147, v144, v145
	v_mul_f32_e32 v35, v196, v33
	v_mul_f32_e32 v33, v34, v33
	v_cmp_gt_f32_e64 s[18:19], s81, v147
	v_mul_f32_e32 v146, v146, v33
	s_cmp_eq_u64 s[18:19], exec
	v_mul_f32_e32 v32, v32, v146
	s_cselect_b64 s[6:7], -1, 0
	v_mul_f32_e32 v34, v195, v33
	v_mul_f32_e32 v33, v194, v146
	v_mul_f32_e32 v32, v193, v32
	s_and_b64 s[6:7], s[6:7], exec

.Lsb_joinB:
	v_mov_b32_e32 v149, v51
	v_mov_b32_e32 v57, v51
	s_nop 1
	v_permlane32_swap_b32_e32 v57, v149
	v_cndmask_b32_e64 v57, v149, v57, s[98:99]
	v_mul_f32_e32 v52, v52, v63
	v_mov_b32_e32 v149, v52
	v_mov_b32_e32 v209, v52
	s_nop 1
	v_permlane32_swap_b32_e32 v209, v149
	v_cndmask_b32_e64 v209, v149, v209, s[98:99]
	v_mov_b32_e32 v149, v145
	v_mov_b32_e32 v49, v145
	s_nop 1
	v_permlane32_swap_b32_e32 v49, v149
	v_cndmask_b32_e64 v49, v149, v49, s[98:99]
	s_waitcnt lgkmcnt(2)
	v_mul_f32_e32 v63, v147, v57
	v_cndmask_b32_e64 v210, v147, v63, s[10:11]
	v_mul_f32_e32 v51, v51, v57
	v_mul_f32_e32 v61, v61, v210
	v_mul_f32_e32 v51, v147, v51
	v_mul_f32_e32 v59, v59, v61
	s_waitcnt lgkmcnt(1)
	v_mul_f32_e32 v57, v51, v209
	v_mul_f32_e32 v63, v62, v210
	v_mul_f32_e32 v62, v208, v61
	v_mul_f32_e32 v61, v60, v59
	v_mul_f32_e32 v59, v207, v59
	v_cndmask_b32_e64 v57, v51, v57, s[10:11]
	v_mul_f32_e32 v60, v206, v59
	v_mul_f32_e32 v59, v58, v57
	v_mul_f32_e32 v57, v205, v57
	v_mul_f32_e32 v53, v53, v57
	v_mul_f32_e32 v58, v204, v57
	v_mul_f32_e32 v57, v54, v53
	v_mul_f32_e32 v53, v56, v53
	v_mul_f32_e32 v147, v52, v209
	v_mul_f32_e32 v56, v55, v53
	v_pk_mul_f32 v[52:53], v[146:147], v[50:51]
	s_waitcnt lgkmcnt(0)
	v_pk_mul_f32 v[54:55], v[144:145], v[48:49]
	v_mul_f32_e32 v49, v53, v49
	v_pk_mul_f32 v[144:145], v[54:55], v[52:53]
	v_mov_b32_e32 v149, v144
	v_mov_b32_e32 v147, v144
	s_nop 1
	v_permlane32_swap_b32_e32 v147, v149
	v_cndmask_b32_e64 v147, v149, v147, s[98:99]
	v_cndmask_b32_e64 v49, v53, v49, s[10:11]
	v_mul_f32_e32 v55, v203, v49
	v_mul_f32_e32 v49, v202, v49
	v_mul_f32_e32 v54, v201, v49
	v_mul_f32_e32 v49, v200, v49
	v_mul_f32_e32 v53, v199, v49
	v_mul_f32_e32 v49, v198, v49
	v_mul_f32_e32 v52, v197, v49
	s_waitcnt lgkmcnt(0)
	v_mul_f32_e32 v49, v145, v147
	v_mul_f32_e32 v144, v144, v147
	v_cndmask_b32_e64 v49, v145, v49, s[10:11]
	v_mul_f32_e32 v147, v144, v145
	v_mul_f32_e32 v51, v196, v49
	v_mul_f32_e32 v49, v50, v49
	v_cmp_gt_f32_e64 s[14:15], s81, v147
	v_mul_f32_e32 v146, v146, v49
	s_cmp_eq_u64 s[14:15], exec
	v_mul_f32_e32 v48, v48, v146
	s_cselect_b64 s[6:7], -1, 0
	v_mul_f32_e32 v50, v195, v49
	v_mul_f32_e32 v49, v194, v146
	v_mul_f32_e32 v48, v193, v48
	s_orn2_b64 s[18:19], s[6:7], exec
	s_or_b64 exec, exec, s[40:41]
	s_and_saveexec_b64 s[14:15], s[38:39]
	s_cbranch_execz .LBB0_997
